# FFO y_old touch burst removed (full-mask units use the straight-line epilogue; for split units 7/8 of the touched rows were never read); otherwise v043
# baseline (speedup 1.0000x reference)
.LBB0_1024:
	s_add_u32 s18, s12, 0x1aa00000
	s_addc_u32 s19, s13, 0
	s_mul_hi_i32 s9, s8, 0x12000
	s_mul_i32 s8, s8, 0x12000
	s_add_u32 s8, s12, s8
	s_addc_u32 s9, s13, s9
	s_add_u32 s16, s8, 0x20000
	v_readlane_b32 s8, v254, 38
	s_addc_u32 s17, s9, 0
	s_and_b64 vcc, exec, s[6:7]
	v_mov_b32_e32 v2, s8
	ds_read_b32 v2, v2
	v_readlane_b32 s8, v254, 39
	s_waitcnt lgkmcnt(0)
	s_nop 0
	v_mov_b32_e32 v2, s8
	ds_read_b32 v2, v2
	v_readlane_b32 s8, v254, 40
	s_waitcnt lgkmcnt(0)
	s_nop 0
	v_mov_b32_e32 v2, s8
	ds_read_b32 v2, v2
	v_readlane_b32 s8, v254, 41
	s_waitcnt lgkmcnt(0)
	s_nop 0
	v_mov_b32_e32 v2, s8
	ds_read_b32 v2, v2
	v_readlane_b32 s8, v255, 18
	s_waitcnt lgkmcnt(0)
	v_lshl_add_u32 v2, v191, 3, s70
	v_lshl_add_u32 v178, s3, 8, v2
	v_add_u32_e32 v4, s8, v189
	v_lshl_add_u32 v180, s4, 8, v4
	s_cbranch_vccnz .LBB0_1082
	s_cmp_eq_u32 s84, 0xff
	s_cbranch_scc1 .Lrfast_ffo
	v_ashrrev_i32_e32 v181, 31, v180
	v_lshlrev_b64 v[206:207], 12, v[180:181]
	s_mov_b64 s[0:1], 0x10000
	v_lshl_add_u64 v[212:213], v[206:207], 0, s[0:1]
	s_mov_b64 s[0:1], 0x20000
	v_ashrrev_i32_e32 v179, 31, v178
	v_lshl_add_u64 v[210:211], v[206:207], 0, s[0:1]
	s_mov_b64 s[0:1], 0x30000
	v_lshl_add_u64 v[182:183], v[178:179], 1, s[18:19]
	v_lshl_add_u64 v[208:209], v[206:207], 0, s[0:1]
	v_lshl_add_u64 v[204:205], v[182:183], 0, v[212:213]
	v_lshl_add_u64 v[184:185], v[182:183], 0, v[208:209]
	v_lshl_add_u64 v[186:187], v[182:183], 0, v[210:211]
	global_load_dwordx4 v[170:173], v[204:205], off
	global_load_dwordx4 v[166:169], v[186:187], off
	global_load_dwordx4 v[158:161], v[184:185], off
	v_lshlrev_b32_e32 v4, 3, v4
	v_add_u32_e32 v214, 0, v4
	v_add_u32_e32 v4, 0x20000, v214
	ds_read2_b64 v[174:177], v4 offset1:16
	v_lshl_add_u32 v2, v2, 2, 0
	v_add_u32_e32 v197, 0x20800, v2
	v_add_u32_e32 v199, 0x20c00, v2
	ds_read2_b64 v[162:165], v4 offset0:32 offset1:48
	s_waitcnt lgkmcnt(0)
	v_mul_f32_e32 v201, 0x3a000000, v174
	v_mul_f32_e32 v5, v201, v201
	v_fma_f32 v5, v175, s72, -v5
	v_add_f32_e32 v5, 0x3727c5ac, v5
	s_waitcnt vmcnt(0)
	ds_read_b128 v[150:153], v197
	ds_read_b128 v[142:145], v197 offset:16
	ds_read_b128 v[154:157], v199
	ds_read_b128 v[146:149], v199 offset:16
	v_rsq_f32_e32 v174, v5
	s_and_b32 s6, s84, 1
	s_bitcmp1_b32 s84, 0
	s_cselect_b64 s[0:1], -1, 0
	s_cmp_eq_u32 s6, 0
	s_cbranch_scc1 .LBB0_1048
	v_lshl_add_u64 v[4:5], v[182:183], 0, v[206:207]
	global_load_dwordx4 v[134:137], v[4:5], off
	s_waitcnt vmcnt(0)
	v_lshlrev_b32_e32 v2, 16, v134
	v_and_b32_e32 v4, 0xffff0000, v134
	v_lshlrev_b32_e32 v134, 16, v135
	v_and_b32_e32 v135, 0xffff0000, v135
	v_lshlrev_b32_e32 v175, 16, v136
	v_sub_f32_e32 v5, v4, v201
	v_sub_f32_e32 v4, v2, v201
	v_sub_f32_e32 v135, v135, v201
	v_sub_f32_e32 v134, v134, v201
	v_pk_mul_f32 v[134:135], v[174:175], v[134:135] op_sel_hi:[0,1]
	v_pk_mul_f32 v[4:5], v[174:175], v[4:5] op_sel_hi:[0,1]
	s_waitcnt lgkmcnt(1)
	v_pk_fma_f32 v[4:5], v[150:151], v[4:5], v[154:155]
	v_pk_fma_f32 v[134:135], v[152:153], v[134:135], v[156:157]
	v_and_b32_e32 v136, 0xffff0000, v136
	v_lshlrev_b32_e32 v203, 16, v137
	v_and_b32_e32 v137, 0xffff0000, v137
	v_pk_mul_f32 v[134:135], v[134:135], s[76:77] op_sel_hi:[1,0]
	v_pk_mul_f32 v[4:5], v[4:5], s[76:77] op_sel_hi:[1,0]
	v_pk_fma_f32 v[140:141], v[128:129], 0.5, v[134:135] op_sel_hi:[1,0,1]
	v_pk_fma_f32 v[138:139], v[126:127], 0.5, v[4:5] op_sel_hi:[1,0,1]
	v_sub_f32_e32 v5, v136, v201
	v_sub_f32_e32 v4, v175, v201
	v_sub_f32_e32 v135, v137, v201
	v_sub_f32_e32 v134, v203, v201
	v_pk_mul_f32 v[134:135], v[174:175], v[134:135] op_sel_hi:[0,1]
	v_pk_mul_f32 v[4:5], v[174:175], v[4:5] op_sel_hi:[0,1]
	s_waitcnt lgkmcnt(0)
	v_pk_fma_f32 v[4:5], v[142:143], v[4:5], v[146:147]
	v_pk_fma_f32 v[134:135], v[144:145], v[134:135], v[148:149]
	v_pk_mul_f32 v[4:5], v[4:5], s[76:77] op_sel_hi:[1,0]
	v_pk_mul_f32 v[134:135], v[134:135], s[76:77] op_sel_hi:[1,0]
	v_pk_fma_f32 v[216:217], v[130:131], 0.5, v[4:5] op_sel_hi:[1,0,1]
	v_pk_fma_f32 v[218:219], v[132:133], 0.5, v[134:135] op_sel_hi:[1,0,1]
	v_pk_add_f32 v[134:135], v[138:139], v[216:217]
	v_pk_add_f32 v[4:5], v[140:141], v[218:219]
	v_pk_mul_f32 v[136:137], v[216:217], v[216:217]
	v_pk_mul_f32 v[222:223], v[218:219], v[218:219]
	v_pk_fma_f32 v[136:137], v[138:139], v[138:139], v[136:137]
	v_pk_fma_f32 v[222:223], v[140:141], v[140:141], v[222:223]
	v_pk_mov_b32 v[224:225], v[134:135], v[4:5] op_sel:[1,0]
	v_mov_b32_e32 v135, v5
	v_pk_add_f32 v[4:5], v[224:225], v[134:135]
	v_pk_mov_b32 v[134:135], v[136:137], v[222:223] op_sel:[1,0]
	v_mov_b32_e32 v137, v223
	v_pk_add_f32 v[134:135], v[134:135], v[136:137]
	v_add_f32_e32 v2, v4, v5
	v_pk_add_f32 v[134:135], v[134:135], v[134:135] op_sel:[0,1] op_sel_hi:[1,0]
	v_cvt_pk_bf16_f32 v138, v138, v139
	v_cvt_pk_bf16_f32 v139, v140, v141
	v_cvt_pk_bf16_f32 v140, v216, v217
	v_lshl_add_u64 v[216:217], s[18:19], 0, v[206:207]
	v_add_f32_e32 v2, 0, v2
	v_mov_b32_e32 v4, v3
	v_mov_b32_e32 v5, v3
	v_mov_b32_e32 v135, v3
	v_mov_b32_e32 v136, v3
	v_mov_b32_e32 v137, v3
	v_cvt_pk_bf16_f32 v141, v218, v219
	v_lshl_add_u64 v[216:217], v[178:179], 1, v[216:217]
	global_store_dwordx4 v[216:217], v[138:141], off
	s_branch .LBB0_1049
